# retention state scan: the 32 per-chunk loads of each element issued up front instead of one dependent load per step
# speedup vs baseline: 1.0015x; 1.0011x over previous
.LBB0_417:
	s_waitcnt vmcnt(0)
	s_mov_b64 s[4:5], 0x4000
	v_lshl_add_u64 v[14:15], v[0:1], 0, s[28:29]
	v_add_co_u32_e32 v14, vcc, 0xf500000, v14
	s_nop 1
	v_addc_co_u32_e32 v15, vcc, 0, v15, vcc
	global_load_dword v40, v[14:15], off
	v_lshl_add_u64 v[14:15], v[14:15], 0, s[4:5]
	global_load_dword v41, v[14:15], off
	v_lshl_add_u64 v[14:15], v[14:15], 0, s[4:5]
	global_load_dword v42, v[14:15], off
	v_lshl_add_u64 v[14:15], v[14:15], 0, s[4:5]
	global_load_dword v43, v[14:15], off
	v_lshl_add_u64 v[14:15], v[14:15], 0, s[4:5]
	global_load_dword v44, v[14:15], off
	v_lshl_add_u64 v[14:15], v[14:15], 0, s[4:5]
	global_load_dword v45, v[14:15], off
	v_lshl_add_u64 v[14:15], v[14:15], 0, s[4:5]
	global_load_dword v46, v[14:15], off
	v_lshl_add_u64 v[14:15], v[14:15], 0, s[4:5]
	global_load_dword v47, v[14:15], off
	v_lshl_add_u64 v[14:15], v[14:15], 0, s[4:5]
	global_load_dword v48, v[14:15], off
	v_lshl_add_u64 v[14:15], v[14:15], 0, s[4:5]
	global_load_dword v49, v[14:15], off
	v_lshl_add_u64 v[14:15], v[14:15], 0, s[4:5]
	global_load_dword v50, v[14:15], off
	v_lshl_add_u64 v[14:15], v[14:15], 0, s[4:5]
	global_load_dword v51, v[14:15], off
	v_lshl_add_u64 v[14:15], v[14:15], 0, s[4:5]
	global_load_dword v52, v[14:15], off
	v_lshl_add_u64 v[14:15], v[14:15], 0, s[4:5]
	global_load_dword v53, v[14:15], off
	v_lshl_add_u64 v[14:15], v[14:15], 0, s[4:5]
	global_load_dword v54, v[14:15], off
	v_lshl_add_u64 v[14:15], v[14:15], 0, s[4:5]
	global_load_dword v55, v[14:15], off
	v_lshl_add_u64 v[14:15], v[14:15], 0, s[4:5]
	global_load_dword v56, v[14:15], off
	v_lshl_add_u64 v[14:15], v[14:15], 0, s[4:5]
	global_load_dword v57, v[14:15], off
	v_lshl_add_u64 v[14:15], v[14:15], 0, s[4:5]
	global_load_dword v58, v[14:15], off
	v_lshl_add_u64 v[14:15], v[14:15], 0, s[4:5]
	global_load_dword v59, v[14:15], off
	v_lshl_add_u64 v[14:15], v[14:15], 0, s[4:5]
	global_load_dword v60, v[14:15], off
	v_lshl_add_u64 v[14:15], v[14:15], 0, s[4:5]
	global_load_dword v61, v[14:15], off
	v_lshl_add_u64 v[14:15], v[14:15], 0, s[4:5]
	global_load_dword v62, v[14:15], off
	v_lshl_add_u64 v[14:15], v[14:15], 0, s[4:5]
	global_load_dword v63, v[14:15], off
	v_lshl_add_u64 v[14:15], v[14:15], 0, s[4:5]
	global_load_dword v64, v[14:15], off
	v_lshl_add_u64 v[14:15], v[14:15], 0, s[4:5]
	global_load_dword v65, v[14:15], off
	v_lshl_add_u64 v[14:15], v[14:15], 0, s[4:5]
	global_load_dword v66, v[14:15], off
	v_lshl_add_u64 v[14:15], v[14:15], 0, s[4:5]
	global_load_dword v67, v[14:15], off
	v_lshl_add_u64 v[14:15], v[14:15], 0, s[4:5]
	global_load_dword v68, v[14:15], off
	v_lshl_add_u64 v[14:15], v[14:15], 0, s[4:5]
	global_load_dword v69, v[14:15], off
	v_lshl_add_u64 v[14:15], v[14:15], 0, s[4:5]
	global_load_dword v70, v[14:15], off
	v_lshl_add_u64 v[14:15], v[14:15], 0, s[4:5]
	global_load_dword v71, v[14:15], off
	s_mov_b64 s[4:5], 0x2000
	v_lshl_add_u64 v[12:13], v[2:3], 0, s[28:29]
	v_add_co_u32_e32 v12, vcc, 0x800000, v12
	s_nop 1
	v_addc_co_u32_e32 v13, vcc, 0, v13, vcc
	v_cvt_pk_bf16_f32 v80, v11, v7
	s_waitcnt vmcnt(31)
	v_fmac_f32_e32 v40, v10, v11
	v_cvt_pk_bf16_f32 v81, v40, v7
	s_waitcnt vmcnt(30)
	v_fmac_f32_e32 v41, v10, v40
	v_cvt_pk_bf16_f32 v82, v41, v7
	s_waitcnt vmcnt(29)
	v_fmac_f32_e32 v42, v10, v41
	v_cvt_pk_bf16_f32 v83, v42, v7
	s_waitcnt vmcnt(28)
	v_fmac_f32_e32 v43, v10, v42
	v_cvt_pk_bf16_f32 v84, v43, v7
	s_waitcnt vmcnt(27)
	v_fmac_f32_e32 v44, v10, v43
	v_cvt_pk_bf16_f32 v85, v44, v7
	s_waitcnt vmcnt(26)
	v_fmac_f32_e32 v45, v10, v44
	v_cvt_pk_bf16_f32 v86, v45, v7
	s_waitcnt vmcnt(25)
	v_fmac_f32_e32 v46, v10, v45
	v_cvt_pk_bf16_f32 v87, v46, v7
	s_waitcnt vmcnt(24)
	v_fmac_f32_e32 v47, v10, v46
	v_cvt_pk_bf16_f32 v88, v47, v7
	s_waitcnt vmcnt(23)
	v_fmac_f32_e32 v48, v10, v47
	v_cvt_pk_bf16_f32 v89, v48, v7
	s_waitcnt vmcnt(22)
	v_fmac_f32_e32 v49, v10, v48
	v_cvt_pk_bf16_f32 v90, v49, v7
	s_waitcnt vmcnt(21)
	v_fmac_f32_e32 v50, v10, v49
	v_cvt_pk_bf16_f32 v91, v50, v7
	s_waitcnt vmcnt(20)
	v_fmac_f32_e32 v51, v10, v50
	v_cvt_pk_bf16_f32 v92, v51, v7
	s_waitcnt vmcnt(19)
	v_fmac_f32_e32 v52, v10, v51
	v_cvt_pk_bf16_f32 v93, v52, v7
	s_waitcnt vmcnt(18)
	v_fmac_f32_e32 v53, v10, v52
	v_cvt_pk_bf16_f32 v94, v53, v7
	s_waitcnt vmcnt(17)
	v_fmac_f32_e32 v54, v10, v53
	v_cvt_pk_bf16_f32 v95, v54, v7
	s_waitcnt vmcnt(16)
	v_fmac_f32_e32 v55, v10, v54
	v_cvt_pk_bf16_f32 v96, v55, v7
	s_waitcnt vmcnt(15)
	v_fmac_f32_e32 v56, v10, v55
	v_cvt_pk_bf16_f32 v97, v56, v7
	s_waitcnt vmcnt(14)
	v_fmac_f32_e32 v57, v10, v56
	v_cvt_pk_bf16_f32 v98, v57, v7
	s_waitcnt vmcnt(13)
	v_fmac_f32_e32 v58, v10, v57
	v_cvt_pk_bf16_f32 v99, v58, v7
	s_waitcnt vmcnt(12)
	v_fmac_f32_e32 v59, v10, v58
	v_cvt_pk_bf16_f32 v100, v59, v7
	s_waitcnt vmcnt(11)
	v_fmac_f32_e32 v60, v10, v59
	v_cvt_pk_bf16_f32 v101, v60, v7
	s_waitcnt vmcnt(10)
	v_fmac_f32_e32 v61, v10, v60
	v_cvt_pk_bf16_f32 v102, v61, v7
	s_waitcnt vmcnt(9)
	v_fmac_f32_e32 v62, v10, v61
	v_cvt_pk_bf16_f32 v103, v62, v7
	s_waitcnt vmcnt(8)
	v_fmac_f32_e32 v63, v10, v62
	v_cvt_pk_bf16_f32 v104, v63, v7
	s_waitcnt vmcnt(7)
	v_fmac_f32_e32 v64, v10, v63
	v_cvt_pk_bf16_f32 v105, v64, v7
	s_waitcnt vmcnt(6)
	v_fmac_f32_e32 v65, v10, v64
	v_cvt_pk_bf16_f32 v106, v65, v7
	s_waitcnt vmcnt(5)
	v_fmac_f32_e32 v66, v10, v65
	v_cvt_pk_bf16_f32 v107, v66, v7
	s_waitcnt vmcnt(4)
	v_fmac_f32_e32 v67, v10, v66
	v_cvt_pk_bf16_f32 v108, v67, v7
	s_waitcnt vmcnt(3)
	v_fmac_f32_e32 v68, v10, v67
	v_cvt_pk_bf16_f32 v109, v68, v7
	s_waitcnt vmcnt(2)
	v_fmac_f32_e32 v69, v10, v68
	v_cvt_pk_bf16_f32 v110, v69, v7
	s_waitcnt vmcnt(1)
	v_fmac_f32_e32 v70, v10, v69
	v_cvt_pk_bf16_f32 v111, v70, v7
	s_waitcnt vmcnt(0)
	v_fmac_f32_e32 v71, v10, v70
	global_store_short v[12:13], v80, off
	v_lshl_add_u64 v[12:13], v[12:13], 0, s[4:5]
	global_store_short v[12:13], v81, off
	v_lshl_add_u64 v[12:13], v[12:13], 0, s[4:5]
	global_store_short v[12:13], v82, off
	v_lshl_add_u64 v[12:13], v[12:13], 0, s[4:5]
	global_store_short v[12:13], v83, off
	v_lshl_add_u64 v[12:13], v[12:13], 0, s[4:5]
	global_store_short v[12:13], v84, off
	v_lshl_add_u64 v[12:13], v[12:13], 0, s[4:5]
	global_store_short v[12:13], v85, off
	v_lshl_add_u64 v[12:13], v[12:13], 0, s[4:5]
	global_store_short v[12:13], v86, off
	v_lshl_add_u64 v[12:13], v[12:13], 0, s[4:5]
	global_store_short v[12:13], v87, off
	v_lshl_add_u64 v[12:13], v[12:13], 0, s[4:5]
	global_store_short v[12:13], v88, off
	v_lshl_add_u64 v[12:13], v[12:13], 0, s[4:5]
	global_store_short v[12:13], v89, off
	v_lshl_add_u64 v[12:13], v[12:13], 0, s[4:5]
	global_store_short v[12:13], v90, off
	v_lshl_add_u64 v[12:13], v[12:13], 0, s[4:5]
	global_store_short v[12:13], v91, off
	v_lshl_add_u64 v[12:13], v[12:13], 0, s[4:5]
	global_store_short v[12:13], v92, off
	v_lshl_add_u64 v[12:13], v[12:13], 0, s[4:5]
	global_store_short v[12:13], v93, off
	v_lshl_add_u64 v[12:13], v[12:13], 0, s[4:5]
	global_store_short v[12:13], v94, off
	v_lshl_add_u64 v[12:13], v[12:13], 0, s[4:5]
	global_store_short v[12:13], v95, off
	v_lshl_add_u64 v[12:13], v[12:13], 0, s[4:5]
	global_store_short v[12:13], v96, off
	v_lshl_add_u64 v[12:13], v[12:13], 0, s[4:5]
	global_store_short v[12:13], v97, off
	v_lshl_add_u64 v[12:13], v[12:13], 0, s[4:5]
	global_store_short v[12:13], v98, off
	v_lshl_add_u64 v[12:13], v[12:13], 0, s[4:5]
	global_store_short v[12:13], v99, off
	v_lshl_add_u64 v[12:13], v[12:13], 0, s[4:5]
	global_store_short v[12:13], v100, off
	v_lshl_add_u64 v[12:13], v[12:13], 0, s[4:5]
	global_store_short v[12:13], v101, off
	v_lshl_add_u64 v[12:13], v[12:13], 0, s[4:5]
	global_store_short v[12:13], v102, off
	v_lshl_add_u64 v[12:13], v[12:13], 0, s[4:5]
	global_store_short v[12:13], v103, off
	v_lshl_add_u64 v[12:13], v[12:13], 0, s[4:5]
	global_store_short v[12:13], v104, off
	v_lshl_add_u64 v[12:13], v[12:13], 0, s[4:5]
	global_store_short v[12:13], v105, off
	v_lshl_add_u64 v[12:13], v[12:13], 0, s[4:5]
	global_store_short v[12:13], v106, off
	v_lshl_add_u64 v[12:13], v[12:13], 0, s[4:5]
	global_store_short v[12:13], v107, off
	v_lshl_add_u64 v[12:13], v[12:13], 0, s[4:5]
	global_store_short v[12:13], v108, off
	v_lshl_add_u64 v[12:13], v[12:13], 0, s[4:5]
	global_store_short v[12:13], v109, off
	v_lshl_add_u64 v[12:13], v[12:13], 0, s[4:5]
	global_store_short v[12:13], v110, off
	v_lshl_add_u64 v[12:13], v[12:13], 0, s[4:5]
	global_store_short v[12:13], v111, off
	v_add_u32_e32 v4, s33, v4
	v_cmp_lt_i32_e32 vcc, s41, v4
	s_or_b64 s[8:9], vcc, s[8:9]
	v_add_u16_e32 v5, s42, v5
	s_andn2_b64 exec, exec, s[8:9]
	s_cbranch_execnz .LBB0_416
